# WKV scan chunk loop: wait only for the operand loads (vmcnt(1)), not for the previous chunk's y store
# baseline (speedup 1.0000x reference)
; __device__ __forceinline__ float red16(float x) { x += dppf(x, 0); x += dppf(x, 1); x += dppf(x, 2); x += dppf(x, 3); return x; }
; __device__ __forceinline__ void scan_phase(const Params& p, int j, unsigned char* smem) {
;     ...
;             {
;                 const f32x4 y4 = *(const f32x4*)(YB + tp * 64 + k4), v4 = *(const f32x4*)(VB + tp * 64 + k4), g4 = *(const f32x4*)(GB + tp * 64 + k4);
;                 const float mu = red16((y4[0] + y4[1]) + (y4[2] + y4[3])) * (1.0f / 64.0f);
;                 float q = 0.f;
; #pragma unroll
;                 for (int i = 0; i < 4; ++i) { const float d = y4[i] - mu; q += d * d; }
;                 const float rstd = rsqrtf(red16(q) * (1.0f / 64.0f) + 64e-5f);
;                 const float bon = BON[tp];
;                 float o[4];
; #pragma unroll
;                 for (int i = 0; i < 4; ++i) o[i] = ((y4[i] - mu) * rstd * c_lg[i] + c_lb[i] + bon * v4[i]) * g4[i];
;                 u32x2 w; w.x = pk2(o[0], o[1]); w.y = pk2(o[2], o[3]);
;                 *(u32x2*)(y16 + ((size_t)(b * 2048 + ch * 16 + tp)) * 1024 + col) = w;
;             }
;         }
.LBB0_504:
	v_lshl_add_u32 v23, v58, 2, v23
	v_lshl_add_u32 v64, v56, 2, v23
	s_waitcnt lgkmcnt(0)
	s_barrier
	ds_read_b128 v[64:67], v64 offset:28672
	v_add_u32_e32 v23, v23, v61
	ds_read_b32 v72, v23 offset:32768
	s_cmpk_eq_i32 s6, 0x80
	s_waitcnt lgkmcnt(1)
	v_mov_b32_e32 v68, v65
	v_mov_b32_e32 v69, v66
	v_mov_b32_e32 v70, v64
	v_mov_b32_e32 v71, v67
	v_pk_add_f32 v[68:69], v[68:69], v[70:71]
	s_nop 0
	v_add_f32_e32 v23, v68, v69
	s_nop 1
	v_add_f32_dpp v23, v23, v23 quad_perm:[1,0,3,2] row_mask:0xf bank_mask:0xf bound_ctrl:1
	s_nop 1
	v_add_f32_dpp v23, v23, v23 quad_perm:[2,3,0,1] row_mask:0xf bank_mask:0xf bound_ctrl:1
	s_nop 1
	v_add_f32_dpp v23, v23, v23 row_half_mirror row_mask:0xf bank_mask:0xf bound_ctrl:1
	s_nop 1
	v_add_f32_dpp v23, v23, v23 row_mirror row_mask:0xf bank_mask:0xf bound_ctrl:1
	v_mul_f32_e32 v68, 0x3c800000, v23
	v_pk_add_f32 v[76:77], v[64:65], v[68:69] op_sel_hi:[1,0] neg_lo:[0,1] neg_hi:[0,1]
	v_pk_add_f32 v[74:75], v[66:67], v[68:69] op_sel_hi:[1,0] neg_lo:[0,1] neg_hi:[0,1]
	v_pk_mul_f32 v[64:65], v[76:77], v[76:77]
	v_pk_mul_f32 v[66:67], v[74:75], v[74:75]
	v_add_f32_e32 v23, v64, v65
	v_add_f32_e32 v23, v66, v23
	v_add_f32_e32 v23, v67, v23
	s_nop 1
	v_add_f32_dpp v23, v23, v23 quad_perm:[1,0,3,2] row_mask:0xf bank_mask:0xf bound_ctrl:1
	s_nop 1
	v_add_f32_dpp v23, v23, v23 quad_perm:[2,3,0,1] row_mask:0xf bank_mask:0xf bound_ctrl:1
	s_nop 1
	v_add_f32_dpp v23, v23, v23 row_half_mirror row_mask:0xf bank_mask:0xf bound_ctrl:1
	s_nop 1
	v_add_f32_dpp v23, v23, v23 row_mirror row_mask:0xf bank_mask:0xf bound_ctrl:1
	v_fmamk_f32 v23, v23, 0x3c800000, v229
	v_mul_f32_e32 v64, 0x4b800000, v23
	v_cmp_gt_f32_e32 vcc, s48, v23
	s_nop 1
	v_cndmask_b32_e32 v23, v23, v64, vcc
	v_rsq_f32_e32 v23, v23
	ds_read_b128 v[64:67], v63 offset:20480
	ds_read_b128 v[68:71], v63 offset:24576
	v_mul_f32_e32 v63, 0x45800000, v23
	v_cndmask_b32_e32 v78, v23, v63, vcc
	v_pk_mul_f32 v[76:77], v[76:77], v[78:79] op_sel_hi:[1,0]
	s_nop 0
	v_pk_fma_f32 v[76:77], v[12:13], v[76:77], v[16:17]
	s_waitcnt lgkmcnt(1)
	v_pk_fma_f32 v[64:65], v[64:65], v[72:73], v[76:77] op_sel_hi:[1,0,1]
	s_waitcnt lgkmcnt(0)
	v_pk_mul_f32 v[64:65], v[68:69], v[64:65]
	v_pk_mul_f32 v[68:69], v[74:75], v[78:79] op_sel_hi:[1,0]
	v_cvt_pk_f16_f32 v64, v64, v65
	v_pk_fma_f32 v[68:69], v[14:15], v[68:69], v[18:19]
	s_nop 0
	v_pk_fma_f32 v[66:67], v[66:67], v[72:73], v[68:69] op_sel_hi:[1,0,1]
	s_nop 0
	v_pk_mul_f32 v[66:67], v[70:71], v[66:67]
	s_nop 0
	v_cvt_pk_f16_f32 v65, v66, v67
	v_lshl_add_u32 v66, s9, 4, v22
	v_ashrrev_i32_e32 v67, 31, v66
	v_lshlrev_b64 v[66:67], 11, v[66:67]
	v_lshl_add_u64 v[66:67], v[24:25], 0, v[66:67]
	s_mov_b32 s9, s6
	global_store_dwordx2 v[66:67], v[64:65], off
	s_cbranch_scc1 .LBB0_502
	s_waitcnt vmcnt(1)
	s_branch .Lscan_prep

; __device__ __forceinline__ float red16(float x) { x += dppf(x, 0); x += dppf(x, 1); x += dppf(x, 2); x += dppf(x, 3); return x; }
; __device__ __forceinline__ void scan_phase(const Params& p, int j, unsigned char* smem) {
;     ...
;             {
;                 float rf[4], kf[4], vf[4], ef[4], af[4], gf[4];
;                 unpack4(pr[0], rf); unpack4(pr[1], kf); unpack4(pr[2], vf); unpack4(pr[3], ef); unpack4(pr[4], af); unpack4(pr[5], gf);
;                 float kk[4]; float ss = 0.f;
; #pragma unroll
;                 for (int i = 0; i < 4; ++i) { kk[i] = kf[i] * c_kk[i]; ss += kk[i] * kk[i]; }
;                 ss = red16(ss);
;                 const float inv = 1.0f / fmaxf(sqrtf(ss), 1e-12f);
;                 f32x4 A4, B4, W4, K4, R4; float bs = 0.f;
; #pragma unroll
;                 for (int i = 0; i < 4; ++i) {
;                     const float kn = kk[i] * inv;
;                     A4[i] = -kn; B4[i] = kn * af[i];
;                     W4[i] = __expf(-ef[i]);
;                     const float km = kf[i] * (1.0f + (af[i] - 1.0f) * c_ka[i]);
;                     K4[i] = km; R4[i] = rf[i];
;                     bs += rf[i] * km * c_rk[i];
;                 }
;                 bs = red16(bs);
;                 float* o = OPS + tp * 320 + k4;
;                 *(f32x4*)(o) = A4; *(f32x4*)(o + 64) = B4; *(f32x4*)(o + 128) = W4; *(f32x4*)(o + 192) = K4; *(f32x4*)(o + 256) = R4;
;                 *(f32x4*)(VB + tp * 64 + k4) = (f32x4){vf[0], vf[1], vf[2], vf[3]};
;                 *(f32x4*)(GB + tp * 64 + k4) = (f32x4){gf[0], gf[1], gf[2], gf[3]};
;                 if ((lane & 15) == 0) BON[tp] = bs;
;             }
;             if (ch + 1 < 128) {
;                 const size_t go = ((size_t)(b * 2048 + (ch + 1) * 16 + tp)) * 1024 + col;
;                 pr[0] = *(const u32x2*)(r16 + go); pr[1] = *(const u32x2*)(k16 + go); pr[2] = *(const u32x2*)(v16 + go);
;                 pr[3] = *(const u32x2*)(e16 + go); pr[4] = *(const u32x2*)(a16 + go); pr[5] = *(const u32x2*)(g16 + go);
;             }
.Lscan_prep:
	v_cvt_f32_f16_e32 v63, v32
	v_cvt_f32_f16_sdwa v64, v32 dst_sel:DWORD dst_unused:UNUSED_PAD src0_sel:WORD_1
	v_cvt_f32_f16_sdwa v65, v34 dst_sel:DWORD dst_unused:UNUSED_PAD src0_sel:WORD_1
	v_cvt_f32_f16_sdwa v77, v28 dst_sel:DWORD dst_unused:UNUSED_PAD src0_sel:WORD_1
	v_mul_f32_e32 v63, 0xbfb8aa3b, v63
	v_exp_f32_e32 v70, v63
	v_mul_f32_e32 v63, 0xbfb8aa3b, v64
	v_cvt_f32_f16_e32 v64, v34
	v_cvt_f32_f16_e32 v76, v28
	v_cvt_f32_f16_sdwa v67, v26 dst_sel:DWORD dst_unused:UNUSED_PAD src0_sel:WORD_1
	v_cvt_f32_f16_e32 v66, v26
	v_pk_add_f32 v[72:73], v[64:65], -1.0 op_sel_hi:[1,0]
	v_cvt_f32_f16_e32 v78, v33
	v_cvt_f32_f16_sdwa v79, v33 dst_sel:DWORD dst_unused:UNUSED_PAD src0_sel:WORD_1
	v_pk_fma_f32 v[72:73], v[4:5], v[72:73], 1.0 op_sel_hi:[1,1,0]
	v_exp_f32_e32 v71, v63
	v_pk_mul_f32 v[74:75], v[72:73], v[76:77]
	v_pk_mul_f32 v[80:81], v[0:1], v[76:77]
	v_pk_mul_f32 v[72:73], v[74:75], v[66:67]
	v_pk_mul_f32 v[76:77], v[80:81], v[80:81]
	v_fma_f32 v63, v8, v72, 0
	v_fmac_f32_e32 v63, v9, v73
	v_mul_f32_e32 v72, 0xbfb8aa3b, v78
	v_mul_f32_e32 v73, 0xbfb8aa3b, v79
	v_cvt_f32_f16_sdwa v79, v29 dst_sel:DWORD dst_unused:UNUSED_PAD src0_sel:WORD_1
	v_cvt_f32_f16_e32 v78, v29
	v_add_f32_e32 v76, v76, v77
	s_mov_b32 s2, 0xf800000
	v_cvt_f32_f16_sdwa v85, v35 dst_sel:DWORD dst_unused:UNUSED_PAD src0_sel:WORD_1
	v_pk_mul_f32 v[82:83], v[2:3], v[78:79]
	v_cvt_f32_f16_e32 v84, v35
	v_pk_mul_f32 v[86:87], v[82:83], v[82:83]
	v_cvt_f32_f16_sdwa v69, v27 dst_sel:DWORD dst_unused:UNUSED_PAD src0_sel:WORD_1
	v_add_f32_e32 v76, v86, v76
	v_add_f32_e32 v76, v87, v76
	v_cvt_f32_f16_e32 v68, v27
	s_bitcmp1_b32 s9, 0
	v_add_f32_dpp v76, v76, v76 quad_perm:[1,0,3,2] row_mask:0xf bank_mask:0xf bound_ctrl:1
	s_cselect_b32 s10, 0x2040, 0
	v_lshl_add_u32 v23, s10, 2, v54
	v_add_f32_dpp v76, v76, v76 quad_perm:[2,3,0,1] row_mask:0xf bank_mask:0xf bound_ctrl:1
	v_exp_f32_e32 v72, v72
	v_exp_f32_e32 v73, v73
	v_add_f32_dpp v76, v76, v76 row_half_mirror row_mask:0xf bank_mask:0xf bound_ctrl:1
	v_lshlrev_b32_e32 v94, 2, v56
	v_cvt_f32_f16_sdwa v93, v37 dst_sel:DWORD dst_unused:UNUSED_PAD src0_sel:WORD_1
	v_add_f32_dpp v76, v76, v76 row_mirror row_mask:0xf bank_mask:0xf bound_ctrl:1
	v_mul_f32_e32 v77, 0x4f800000, v76
	v_cmp_gt_f32_e32 vcc, s2, v76
	v_cvt_f32_f16_e32 v92, v37
	s_nop 0
	v_cndmask_b32_e32 v86, v76, v77, vcc
	v_sqrt_f32_e32 v87, v86
	v_pk_add_f32 v[76:77], v[84:85], -1.0 op_sel_hi:[1,0]
	v_add_u32_e32 v88, -1, v87
	v_fma_f32 v89, -v88, v87, v86
	v_cmp_ge_f32_e64 s[6:7], 0, v89
	v_add_u32_e32 v89, 1, v87
	v_pk_fma_f32 v[76:77], v[6:7], v[76:77], 1.0 op_sel_hi:[1,1,0]
	v_cndmask_b32_e64 v88, v87, v88, s[6:7]
	v_fma_f32 v87, -v89, v87, v86
	v_cmp_lt_f32_e64 s[6:7], 0, v87
	v_pk_mul_f32 v[76:77], v[76:77], v[78:79]
	s_nop 0
	v_cndmask_b32_e64 v87, v88, v89, s[6:7]
	v_mul_f32_e32 v88, 0x37800000, v87
	v_cndmask_b32_e32 v87, v87, v88, vcc
	v_cmp_class_f32_e32 vcc, v86, v228
	s_nop 1
	v_cndmask_b32_e32 v86, v87, v86, vcc
	v_max_f32_e32 v88, 0x2b8cbccc, v86
	v_div_scale_f32 v89, s[2:3], v88, v88, 1.0
	v_rcp_f32_e32 v90, v89
	v_pk_mul_f32 v[86:87], v[76:77], v[68:69]
	v_fma_f32 v78, -v89, v90, 1.0
	v_fmac_f32_e32 v90, v78, v90
	v_div_scale_f32 v78, vcc, 1.0, v88, 1.0
	v_mul_f32_e32 v79, v78, v90
	v_fmac_f32_e32 v63, v10, v86
	v_fma_f32 v86, -v89, v79, v78
	v_fmac_f32_e32 v79, v86, v90
	v_fma_f32 v78, -v89, v79, v78
	v_div_fmas_f32 v78, v78, v90, v79
	v_fmac_f32_e32 v63, v11, v87
	v_div_fixup_f32 v86, v78, v88, 1.0
	v_pk_mul_f32 v[88:89], v[80:81], v[86:87] op_sel_hi:[1,0]
	v_add_f32_dpp v63, v63, v63 quad_perm:[1,0,3,2] row_mask:0xf bank_mask:0xf bound_ctrl:1
	v_xor_b32_e32 v79, 0x80000000, v89
	v_xor_b32_e32 v78, 0x80000000, v88
	v_add_f32_dpp v63, v63, v63 quad_perm:[2,3,0,1] row_mask:0xf bank_mask:0xf bound_ctrl:1
	v_pk_mul_f32 v[90:91], v[82:83], v[86:87] op_sel_hi:[1,0]
	v_pk_mul_f32 v[82:83], v[88:89], v[64:65]
	v_cvt_f32_f16_sdwa v87, v30 dst_sel:DWORD dst_unused:UNUSED_PAD src0_sel:WORD_1
	v_cvt_f32_f16_e32 v86, v30
	v_cvt_f32_f16_sdwa v89, v31 dst_sel:DWORD dst_unused:UNUSED_PAD src0_sel:WORD_1
	v_cvt_f32_f16_e32 v88, v31
	v_add_f32_dpp v64, v63, v63 row_half_mirror row_mask:0xf bank_mask:0xf bound_ctrl:1
	v_add_u32_e32 v63, v23, v57
	v_xor_b32_e32 v80, 0x80000000, v90
	v_xor_b32_e32 v81, 0x80000000, v91
	v_pk_mul_f32 v[84:85], v[90:91], v[84:85]
	v_cvt_f32_f16_sdwa v91, v36 dst_sel:DWORD dst_unused:UNUSED_PAD src0_sel:WORD_1
	v_cvt_f32_f16_e32 v90, v36
	v_add_u32_e32 v95, v63, v94
	ds_write_b128 v95, v[78:81]
	ds_write_b128 v95, v[82:85] offset:256
	ds_write_b128 v95, v[70:73] offset:512
	ds_write_b128 v95, v[74:77] offset:768
	ds_write_b128 v95, v[66:69] offset:1024
	v_add_u32_e32 v66, v63, v60
	v_mov_b32_dpp v65, v64 row_mirror row_mask:0xf bank_mask:0xf bound_ctrl:1
	v_add_u32_e32 v63, v66, v94
	ds_write_b128 v63, v[86:89] offset:20480
	ds_write_b128 v63, v[90:93] offset:24576
	s_and_saveexec_b64 s[2:3], s[0:1]
	v_add_f32_e32 v64, v64, v65
	v_add_u32_e32 v65, v66, v61
	ds_write_b32 v65, v64 offset:32768
	s_or_b64 exec, exec, s[2:3]
	s_add_i32 s6, s9, 1
	s_cmpk_eq_i32 s9, 0x7f
	s_cbranch_scc1 .LBB0_509
	v_lshl_add_u32 v26, s6, 4, v22
	v_ashrrev_i32_e32 v27, 31, v26
	v_lshlrev_b64 v[36:37], 11, v[26:27]
	v_readlane_b32 s2, v250, 26
	v_lshl_or_b32 v36, v20, 1, v36
	v_readlane_b32 s3, v250, 27
	v_lshl_add_u64 v[26:27], s[42:43], 0, v[36:37]
	v_lshl_add_u64 v[32:33], s[38:39], 0, v[36:37]
	v_lshl_add_u64 v[28:29], s[2:3], 0, v[36:37]
	v_readlane_b32 s2, v253, 43
	v_readlane_b32 s3, v253, 44
	v_lshl_add_u64 v[34:35], s[40:41], 0, v[36:37]
	s_nop 0
	v_lshl_add_u64 v[30:31], s[2:3], 0, v[36:37]
	global_load_dwordx2 v[26:27], v[26:27], off
	s_nop 0
	global_load_dwordx2 v[28:29], v[28:29], off
	s_nop 0
	global_load_dwordx2 v[30:31], v[30:31], off
	v_lshl_add_u64 v[36:37], s[54:55], 0, v[36:37]
	global_load_dwordx2 v[32:33], v[32:33], off
	s_nop 0
	global_load_dwordx2 v[34:35], v[34:35], off
	s_nop 0
	global_load_dwordx2 v[36:37], v[36:37], off
